# v205 + exit counter atomic issued before (overlapping) the final store drain
# speedup vs baseline: 1.0028x; 1.0004x over previous
.LBB0_788:
	s_barrier
	s_and_saveexec_b64 s[0:1], s[96:97]
	s_cbranch_execz .LBB0_792
	s_mov_b64 s[4:5], exec
	v_mbcnt_lo_u32_b32 v1, s4, 0
	v_mbcnt_hi_u32_b32 v1, s5, v1
	v_cmp_eq_u32_e32 vcc, 0, v1
	s_and_saveexec_b64 s[2:3], vcc
	s_cbranch_execz .LBB0_791
	s_bcnt1_i32_b64 s6, s[4:5]
	s_getpc_b64 s[4:5]
	s_add_u32 s4, s4, g_ctl@rel32@lo+772
	s_addc_u32 s5, s5, g_ctl@rel32@hi+780
	v_mov_b32_e32 v2, 0
	v_mov_b32_e32 v3, s6
	global_atomic_add v2, v2, v3, s[4:5] sc0

.LBB0_792:
	s_or_b64 exec, exec, s[0:1]
	s_waitcnt vmcnt(0)
	s_add_i32 s0, 0, 0x25f40
	v_mov_b32_e32 v1, s0
	s_waitcnt lgkmcnt(0)
	s_barrier
	ds_read_b32 v1, v1
	s_waitcnt lgkmcnt(0)
	v_cmp_eq_u32_e32 vcc, 0, v1
	s_cbranch_vccnz .LBB0_797
	v_cmp_gt_u32_e64 s[0:1], 54, v0
	v_cmp_lt_u32_e32 vcc, 53, v0
	v_mov_b64_e32 v[2:3], 0x1000
	s_and_saveexec_b64 s[2:3], vcc
	s_cbranch_execnz .LBB0_798
	s_or_b64 exec, exec, s[2:3]
	s_and_saveexec_b64 s[2:3], s[0:1]
	s_cbranch_execnz .LBB0_799
